# batched epilogue loads + LRU scan loops with batched LDS ops and cooperative 16B stores + part of P0 weight conversion moved into idle WGs of lru_in
# baseline (speedup 1.0000x reference)
; __global__ void __launch_bounds__(NTHR, 2) fwd(Args args) {
;     ...
;                         float p = 1.f, h = 0.f;
; #pragma unroll 8
;                         for (int i = 0; i < 32; ++i) { const int r = dir == 0 ? 32 * sg + i : 255 - (32 * sg + i); const float a = Al[r * 64 + ch], bb = Bl[r * 64 + ch]; p *= a; h = a * h + bb; Al[r * 64 + ch] = p; Bl[r * 64 + ch] = h; }
;                         seg[(sg * 64 + ch) * 2] = p; seg[(sg * 64 + ch) * 2 + 1] = h;
;                         __syncthreads();
;                         float st = hcar, pt = 1.f, ht = 0.f;
; #pragma unroll
;                         for (int k = 0; k < 8; ++k) { const float sp_ = seg[(k * 64 + ch) * 2], sh_ = seg[(k * 64 + ch) * 2 + 1]; if (k < sg) st = sp_ * st + sh_; ht = sp_ * ht + sh_; pt *= sp_; }
.LBB0_1440:
	v_add_u32_e32 v5, s23, v81
	v_lshlrev_b32_e32 v88, 2, v80
	v_add_u32_e32 v6, 7, v4
	v_cndmask_b32_e64 v6, v6, v5, s[18:19]
	v_lshl_or_b32 v96, v6, 8, v88
	v_add_u32_e32 v104, s41, v96
	ds_read_b32 v112, v96
	ds_read_b32 v120, v104
	v_add_u32_e32 v6, 6, v4
	v_add_u32_e32 v7, 1, v5
	v_cndmask_b32_e64 v6, v6, v7, s[18:19]
	v_lshl_or_b32 v97, v6, 8, v88
	v_add_u32_e32 v105, s41, v97
	ds_read_b32 v113, v97
	ds_read_b32 v121, v105
	v_add_u32_e32 v6, 5, v4
	v_add_u32_e32 v7, 2, v5
	v_cndmask_b32_e64 v6, v6, v7, s[18:19]
	v_lshl_or_b32 v98, v6, 8, v88
	v_add_u32_e32 v106, s41, v98
	ds_read_b32 v114, v98
	ds_read_b32 v122, v106
	v_add_u32_e32 v6, 4, v4
	v_add_u32_e32 v7, 3, v5
	v_cndmask_b32_e64 v6, v6, v7, s[18:19]
	v_lshl_or_b32 v99, v6, 8, v88
	v_add_u32_e32 v107, s41, v99
	ds_read_b32 v115, v99
	ds_read_b32 v123, v107
	v_add_u32_e32 v6, 3, v4
	v_add_u32_e32 v7, 4, v5
	v_cndmask_b32_e64 v6, v6, v7, s[18:19]
	v_lshl_or_b32 v100, v6, 8, v88
	v_add_u32_e32 v108, s41, v100
	ds_read_b32 v116, v100
	ds_read_b32 v124, v108
	v_add_u32_e32 v6, 2, v4
	v_add_u32_e32 v7, 5, v5
	v_cndmask_b32_e64 v6, v6, v7, s[18:19]
	v_lshl_or_b32 v101, v6, 8, v88
	v_add_u32_e32 v109, s41, v101
	ds_read_b32 v117, v101
	ds_read_b32 v125, v109
	v_add_u32_e32 v6, 1, v4
	v_add_u32_e32 v7, 6, v5
	v_cndmask_b32_e64 v6, v6, v7, s[18:19]
	v_lshl_or_b32 v102, v6, 8, v88
	v_add_u32_e32 v110, s41, v102
	ds_read_b32 v118, v102
	ds_read_b32 v126, v110
	v_add_u32_e32 v6, 0, v4
	v_add_u32_e32 v7, 7, v5
	v_cndmask_b32_e64 v6, v6, v7, s[18:19]
	v_lshl_or_b32 v103, v6, 8, v88
	v_add_u32_e32 v111, s41, v103
	ds_read_b32 v119, v103
	ds_read_b32 v127, v111
	s_add_i32 s23, s23, 8
	s_waitcnt lgkmcnt(0)
	v_mul_f32_e32 v128, v2, v112
	v_fmac_f32_e32 v120, v3, v112
	v_mul_f32_e32 v129, v128, v113
	v_fmac_f32_e32 v121, v120, v113
	v_mul_f32_e32 v130, v129, v114
	v_fmac_f32_e32 v122, v121, v114
	v_mul_f32_e32 v131, v130, v115
	v_fmac_f32_e32 v123, v122, v115
	v_mul_f32_e32 v132, v131, v116
	v_fmac_f32_e32 v124, v123, v116
	v_mul_f32_e32 v133, v132, v117
	v_fmac_f32_e32 v125, v124, v117
	v_mul_f32_e32 v134, v133, v118
	v_fmac_f32_e32 v126, v125, v118
	v_mul_f32_e32 v135, v134, v119
	v_fmac_f32_e32 v127, v126, v119
	ds_write_b32 v96, v128
	ds_write_b32 v104, v120
	ds_write_b32 v97, v129
	ds_write_b32 v105, v121
	ds_write_b32 v98, v130
	ds_write_b32 v106, v122
	ds_write_b32 v99, v131
	ds_write_b32 v107, v123
	ds_write_b32 v100, v132
	ds_write_b32 v108, v124
	ds_write_b32 v101, v133
	ds_write_b32 v109, v125
	ds_write_b32 v102, v134
	ds_write_b32 v110, v126
	ds_write_b32 v103, v135
	ds_write_b32 v111, v127
	v_mov_b32_e32 v2, v135
	v_mov_b32_e32 v3, v127
	v_add_u32_e32 v4, -8, v4
	s_cmp_eq_u32 s23, 32
	s_cbranch_scc0 .LBB0_1440
	ds_write_b64 v85, v[2:3]
	s_waitcnt lgkmcnt(0)
	s_barrier
	ds_read2st64_b64 v[2:5], v86 offset1:1
	ds_read2st64_b64 v[6:9], v86 offset0:2 offset1:3
	ds_read2st64_b64 v[14:17], v86 offset0:4 offset1:5
	s_lshl_b32 s22, s22, 8
	s_ashr_i32 s23, s22, 31
	s_waitcnt lgkmcnt(2)
	v_fma_f32 v10, v87, v2, v3
	v_cndmask_b32_e64 v10, v87, v10, s[2:3]
	v_fma_f32 v11, v10, v4, v5
	v_cndmask_b32_e64 v10, v10, v11, s[4:5]
	s_waitcnt lgkmcnt(1)
	v_fma_f32 v11, v10, v6, v7
	v_cndmask_b32_e64 v10, v10, v11, s[6:7]
	v_fma_f32 v11, v10, v8, v9
	v_cndmask_b32_e64 v78, v10, v11, s[8:9]
	ds_read2st64_b64 v[10:13], v86 offset0:6 offset1:7
	s_waitcnt lgkmcnt(1)
	v_fma_f32 v79, v78, v14, v15
	v_cndmask_b32_e64 v78, v78, v79, s[10:11]
	v_fma_f32 v79, v78, v16, v17
	v_cndmask_b32_e64 v78, v78, v79, s[12:13]
	s_waitcnt lgkmcnt(0)
	v_fma_f32 v79, v78, v10, v11
	s_add_u32 s22, s46, s22
	v_cndmask_b32_e64 v78, v78, v79, s[14:15]
	s_addc_u32 s23, s43, s23
	v_fma_f32 v79, v78, v12, v13
	s_lshl_b64 s[22:23], s[22:23], 12
	v_cndmask_b32_e64 v89, v78, v79, s[16:17]
	v_lshl_add_u64 v[78:79], v[48:49], 0, s[22:23]
	s_mov_b32 s22, 0
	v_mov_b32_e32 v90, v84
; __device__ __forceinline__ bf16_t f2bf(float x) { return (bf16_t)(cvt_pk_bf16(x, 0.f) & 0xffffu); }
; __global__ void __launch_bounds__(NTHR, 2) fwd(Args args) {
;     ...
;                         float st = hcar, pt = 1.f, ht = 0.f;
; #pragma unroll
;                         for (int k = 0; k < 8; ++k) { const float sp_ = seg[(k * 64 + ch) * 2], sh_ = seg[(k * 64 + ch) * 2 + 1]; if (k < sg) st = sp_ * st + sh_; ht = sp_ * ht + sh_; pt *= sp_; }
;                         const size_t ob = ((size_t)dir * R + pm * 256) * D + ch0 + ch;
; #pragma unroll 8
;                         for (int i = 0; i < 32; ++i) { const int r = dir == 0 ? 32 * sg + i : 255 - (32 * sg + i); HF[ob + (size_t)r * D] = f2bf(Bl[r * 64 + ch] + Al[r * 64 + ch] * st); }
;                         hcar = pt * hcar + ht;
;                         __syncthreads();
.LBB0_1442:
	v_add_u32_e32 v91, s22, v81
	v_add_u32_e32 v92, 7, v90
	v_cndmask_b32_e64 v92, v92, v91, s[18:19]
	v_lshl_or_b32 v96, v92, 8, v88
	v_add_u32_e32 v104, s41, v96
	ds_read_b32 v120, v104
	ds_read_b32 v112, v96
	v_add_u32_e32 v92, 6, v90
	v_add_u32_e32 v93, 1, v91
	v_cndmask_b32_e64 v92, v92, v93, s[18:19]
	v_lshl_or_b32 v97, v92, 8, v88
	v_add_u32_e32 v105, s41, v97
	ds_read_b32 v121, v105
	ds_read_b32 v113, v97
	v_add_u32_e32 v92, 5, v90
	v_add_u32_e32 v93, 2, v91
	v_cndmask_b32_e64 v92, v92, v93, s[18:19]
	v_lshl_or_b32 v98, v92, 8, v88
	v_add_u32_e32 v106, s41, v98
	ds_read_b32 v122, v106
	ds_read_b32 v114, v98
	v_add_u32_e32 v92, 4, v90
	v_add_u32_e32 v93, 3, v91
	v_cndmask_b32_e64 v92, v92, v93, s[18:19]
	v_lshl_or_b32 v99, v92, 8, v88
	v_add_u32_e32 v107, s41, v99
	ds_read_b32 v123, v107
	ds_read_b32 v115, v99
	v_add_u32_e32 v92, 3, v90
	v_add_u32_e32 v93, 4, v91
	v_cndmask_b32_e64 v92, v92, v93, s[18:19]
	v_lshl_or_b32 v100, v92, 8, v88
	v_add_u32_e32 v108, s41, v100
	ds_read_b32 v124, v108
	ds_read_b32 v116, v100
	v_add_u32_e32 v92, 2, v90
	v_add_u32_e32 v93, 5, v91
	v_cndmask_b32_e64 v92, v92, v93, s[18:19]
	v_lshl_or_b32 v101, v92, 8, v88
	v_add_u32_e32 v109, s41, v101
	ds_read_b32 v125, v109
	ds_read_b32 v117, v101
	v_add_u32_e32 v92, 1, v90
	v_add_u32_e32 v93, 6, v91
	v_cndmask_b32_e64 v92, v92, v93, s[18:19]
	v_lshl_or_b32 v102, v92, 8, v88
	v_add_u32_e32 v110, s41, v102
	ds_read_b32 v126, v110
	ds_read_b32 v118, v102
	v_add_u32_e32 v92, 0, v90
	v_add_u32_e32 v93, 7, v91
	v_cndmask_b32_e64 v92, v92, v93, s[18:19]
	v_lshl_or_b32 v103, v92, 8, v88
	v_add_u32_e32 v111, s41, v103
	ds_read_b32 v127, v111
	ds_read_b32 v119, v103
	s_add_i32 s22, s22, 8
	s_waitcnt lgkmcnt(0)
	v_fmac_f32_e32 v120, v89, v112
	v_fmac_f32_e32 v121, v89, v113
	v_fmac_f32_e32 v122, v89, v114
	v_fmac_f32_e32 v123, v89, v115
	v_fmac_f32_e32 v124, v89, v116
	v_fmac_f32_e32 v125, v89, v117
	v_fmac_f32_e32 v126, v89, v118
	v_fmac_f32_e32 v127, v89, v119
	ds_write_b32 v104, v120
	ds_write_b32 v105, v121
	ds_write_b32 v106, v122
	ds_write_b32 v107, v123
	ds_write_b32 v108, v124
	ds_write_b32 v109, v125
	ds_write_b32 v110, v126
	ds_write_b32 v111, v127
	v_add_u32_e32 v90, -8, v90
	s_cmp_eq_u32 s22, 32
	s_cbranch_scc0 .LBB0_1442
	v_fma_f32 v3, 0, v2, v3
	v_fma_f32 v3, v3, v4, v5
	v_mul_f32_e32 v2, v2, v4
	v_fma_f32 v3, v3, v6, v7
	v_mul_f32_e32 v2, v2, v6
	v_fma_f32 v3, v3, v8, v9
	v_mul_f32_e32 v2, v2, v8
	v_fma_f32 v3, v3, v14, v15
	v_mul_f32_e32 v2, v2, v14
	v_fma_f32 v3, v3, v16, v17
	v_mul_f32_e32 v2, v2, v16
	v_fma_f32 v3, v3, v10, v11
	v_mul_f32_e32 v2, v2, v10
	v_mul_f32_e32 v2, v2, v12
	v_fmac_f32_e32 v13, v3, v12
	v_fmac_f32_e32 v13, v87, v2
	s_add_i32 s22, s24, 1
	s_not_b32 s23, s24
	s_cmp_eq_u32 s22, 9
	v_mov_b32_e32 v87, v13
	s_mov_b32 s24, s22
	s_waitcnt lgkmcnt(0)
	s_barrier
	v_lshrrev_b32_e32 v96, 2, v81
	v_lshrrev_b32_e32 v97, 3, v80
	v_add_u32_e32 v96, v96, v97
	v_and_b32_e32 v97, 7, v80
	v_lshlrev_b32_e32 v98, 8, v96
	v_lshl_add_u32 v98, v97, 5, v98
	v_add_u32_e32 v98, s41, v98
	ds_read_b128 v[100:103], v98
	ds_read_b128 v[104:107], v98 offset:16
	ds_read_b128 v[108:111], v98 offset:16384
	ds_read_b128 v[112:115], v98 offset:16400
	ds_read_b128 v[116:119], v98 offset:32768
	ds_read_b128 v[120:123], v98 offset:32784
	ds_read_b128 v[124:127], v98 offset:49152
	ds_read_b128 v[128:131], v98 offset:49168
	v_lshlrev_b32_e32 v99, 1, v80
	v_mov_b32_e32 v133, 0
	v_lshlrev_b32_e32 v132, 12, v96
	v_lshl_add_u32 v132, v97, 4, v132
	v_sub_u32_e32 v132, v132, v99
	v_ashrrev_i32_e32 v133, 31, v132
	v_lshl_add_u64 v[134:135], v[78:79], 0, v[132:133]
	s_mov_b64 s[98:99], 0x40000
	v_lshl_add_u64 v[136:137], v[134:135], 0, s[98:99]
	v_lshl_add_u64 v[138:139], v[136:137], 0, s[98:99]
	v_lshl_add_u64 v[140:141], v[138:139], 0, s[98:99]
	s_waitcnt lgkmcnt(6)
	v_cvt_pk_bf16_f32 v100, v100, v101
	v_cvt_pk_bf16_f32 v101, v102, v103
	v_cvt_pk_bf16_f32 v102, v104, v105
	v_cvt_pk_bf16_f32 v103, v106, v107
	global_store_dwordx4 v[134:135], v[100:103], off
	s_waitcnt lgkmcnt(4)
	v_cvt_pk_bf16_f32 v108, v108, v109
	v_cvt_pk_bf16_f32 v109, v110, v111
	v_cvt_pk_bf16_f32 v110, v112, v113
	v_cvt_pk_bf16_f32 v111, v114, v115
	global_store_dwordx4 v[136:137], v[108:111], off
	s_waitcnt lgkmcnt(2)
	v_cvt_pk_bf16_f32 v116, v116, v117
	v_cvt_pk_bf16_f32 v117, v118, v119
	v_cvt_pk_bf16_f32 v118, v120, v121
	v_cvt_pk_bf16_f32 v119, v122, v123
	global_store_dwordx4 v[138:139], v[116:119], off
	s_waitcnt lgkmcnt(0)
	v_cvt_pk_bf16_f32 v124, v124, v125
	v_cvt_pk_bf16_f32 v125, v126, v127
	v_cvt_pk_bf16_f32 v126, v128, v129
	v_cvt_pk_bf16_f32 v127, v130, v131
	global_store_dwordx4 v[140:141], v[124:127], off
	s_barrier
	s_cmp_eq_u32 s24, 9
	s_cbranch_scc0 .LBB0_1432
	s_add_i32 s33, s33, s40
	s_cmpk_gt_i32 s33, 0xff
	s_cbranch_scc0 .LBB0_1431
